# ssm carry items run at the start of the M3 step with a per-layer done counter and device-scope stores, the separate M2 step and its grid barrier removed; ssm scan step uses scalar f32 ops and d16_hi L
# speedup vs baseline: 1.0053x; 1.0047x over previous
; template <bool DRY>
; DI void run_phase(const CP& p, int ph, int l, char* smem) {
;     ...
;     case PH_M2:
;       for (int it = b0; it < 64; it += nb) ssm_carry_item(p, l, it, smem);
;       break;
;     case PH_M3:
;       FOR_QUEUE(it, 1024, p.wq + l * 2 + 1 + (DRY ? 32 : 0)) {
;         if (DRY && !((it < 512) ? PROBE_SEL == 5 : PROBE_SEL == 6)) continue;
;         if (it < 512) {
;           const int qt = 63 - (it >> 3), bh = it & 7;
;           attn_item<2>(p, l, bh >> 2, bh & 3, qt, smem);
;         } else {
;           ssm_out_item(p, l, it - 512, smem);
;         }
;       }
.LBB0_317:
	s_andn2_b64 vcc, exec, s[4:5]
	s_cbranch_vccnz .LBB0_661
	s_cmp_lt_i32 s87, 3
	s_mov_b64 s[4:5], -1
	s_cbranch_scc1 .LBB0_471
	s_cmp_lt_i32 s87, 4
	s_cbranch_scc1 .LBB0_390
	s_cmp_gt_i32 s87, 4
	s_cbranch_scc0 .LBB0_193
	s_mov_b32 s99, 2
	s_branch .LBB0_381
.Lm3_entry:
	s_load_dwordx4 s[12:15], s[0:1], 0x168
	s_load_dwordx2 s[6:7], s[0:1], 0x98
	s_load_dwordx2 s[10:11], s[0:1], 0xf8
	s_lshl_b32 s48, s64, 1
	s_lshl_b64 s[4:5], s[48:49], 2
	s_mov_b32 s65, s49
	s_waitcnt lgkmcnt(0)
	s_add_u32 s14, s14, s4
	s_addc_u32 s15, s15, s5
	s_lshl_b64 s[28:29], s[64:65], 4
	s_lshl_b64 s[4:5], s[64:65], 17
	s_add_u32 s30, s10, s4
	s_addc_u32 s31, s11, s5
	s_lshl_b64 s[4:5], s[64:65], 10
	s_load_dwordx4 s[16:19], s[0:1], 0x140
	s_load_dwordx2 s[66:67], s[0:1], 0x158
	s_load_dwordx4 s[20:23], s[0:1], 0x128
	s_load_dwordx4 s[24:27], s[0:1], 0x110
	s_add_u32 s68, s6, s4
	s_addc_u32 s69, s7, s5
	s_waitcnt lgkmcnt(0)
	s_add_u32 s65, s18, 0x6800000
	s_addc_u32 s90, s19, 0
	s_lshl_b32 s4, s64, 2
	s_sub_u32 s4, 0xa0, s4
	s_add_u32 s100, s14, s4
	s_addc_u32 s101, s15, 0
	s_mov_b32 s99, 0
	s_branch .LBB0_325

; DI int get_tid() { int t = __builtin_amdgcn_workitem_id_x(); asm volatile("" : "+v"(t)); return t; }
; DI void ssm_out_item(const CP& p, int l, int item, char* smem) {
;   const int tid = get_tid(), lane = tid & 63, w = tid >> 6, l32 = lane & 31, hh = lane >> 5;
;   const int b = item >> 8, c = item & 255;
;   const size_t tok0 = (size_t)b * S_ + c * 64;
;   u16* sX = (u16*)smem + w * (32 * 136);
;   u16* sY = (u16*)smem + 8 * 32 * 136;
;   float* sSS = (float*)(sY + 64 * 264);
;   const int l16 = lane & 15, q4 = lane >> 4;
; #pragma unroll 1
;   for (int gi = 0; gi < 2; ++gi) {
;     const int g = w * 2 + gi;
;     const fl4 ac = *(const fl4*)(p.ssmc + (((size_t)l * 16 + g) * 64 + lane) * 4);
;     bf16x8 bf_[4];
; #pragma unroll
;     for (int mb = 0; mb < 4; ++mb)
;       bf_[mb] = *(const bf16x8*)(p.bbmat + ((((size_t)l * 16 + g) * 128) + mb * 32 + l32) * 16 + hh * 8);
;     const fl2 c0 = *(const fl2*)(p.cin + ((((size_t)b * NCH + c) * 16 + g) * 64 + lane) * 2);
;     fl2 x = {c0.x, c0.y};
;     const fl2 a_r = {ac.x, ac.x}, a_i = {ac.y, ac.y};
;     bf16x8 cf[4];
; #pragma unroll
;     for (int ks = 0; ks < 4; ++ks)
;       cf[ks] = *(const bf16x8*)(p.cmat + (((size_t)l * 16 + g) * 16 + l16) * 128 + ks * 32 + q4 * 8);
;     const fl4 dsk = *(const fl4*)(p.ssm_d + ((size_t)l * 16 + g) * 16 + q4 * 4);
; #pragma unroll 1
;     for (int sub = 0; sub < 2; ++sub) {
;       {
;         const bf16x8 uf = *(const bf16x8*)(p.R + (tok0 + sub * 32 + l32) * TMW + 1408 + g * 16 + hh * 8);
; template <bool DRY>
; DI void run_phase(const CP& p, int ph, int l, char* smem) {
;     ...
;       FOR_QUEUE(it, 1024, p.wq + l * 2 + 1 + (DRY ? 32 : 0)) {
;         if (DRY && !((it < 512) ? PROBE_SEL == 5 : PROBE_SEL == 6)) continue;
;         if (it < 512) {
;           const int qt = 63 - (it >> 3), bh = it & 7;
;           attn_item<2>(p, l, bh >> 2, bh & 3, qt, smem);
;         } else {
;           ssm_out_item(p, l, it - 512, smem);
.LBB0_329:
	s_or_b64 exec, exec, s[4:5]
	v_mov_b32_e32 v0, s41
	s_waitcnt lgkmcnt(0)
	s_barrier
	ds_read_b32 v0, v0
	s_movk_i32 s4, 0x3ff
	s_waitcnt lgkmcnt(0)
	v_cmp_lt_i32_e32 vcc, s4, v0
	v_readfirstlane_b32 s74, v0
	s_mov_b64 s[4:5], -1
	s_cbranch_vccnz .LBB0_324
	s_cmpk_gt_i32 s74, 0x1ff
	s_cbranch_scc0 .LBB0_344
	s_cmp_eq_u32 s99, 1
	s_cbranch_scc1 .Lcin_ready
.Lcin_poll:
	global_load_dword v0, v33, s[100:101] sc1
	s_waitcnt vmcnt(0)
	v_readfirstlane_b32 s8, v0
	s_cmpk_ge_u32 s8, 0x200
	s_cbranch_scc1 .Lcin_set
	s_sleep 2
	s_branch .Lcin_poll
.Lcin_set:
	s_mov_b32 s99, 1
.Lcin_ready:
	s_add_i32 s4, s74, 0xfffffe00
	s_lshr_b32 s48, s4, 8
	s_and_b32 s8, s74, 0xff
	v_mov_b32_e32 v54, v202
	s_lshl_b64 s[6:7], s[48:49], 14
	s_lshl_b32 s4, s8, 6
	s_or_b32 s6, s6, s4
	v_ashrrev_i32_e32 v59, 6, v54
	s_movk_i32 s4, 0x2200
	v_mul_lo_u32 v0, v59, s4
	s_load_dwordx2 s[4:5], s[0:1], 0x180
	s_load_dwordx2 s[10:11], s[0:1], 0x88
	v_and_b32_e32 v55, 63, v54
	v_bfe_u32 v57, v54, 5, 1
	v_lshlrev_b32_e32 v32, 4, v55
	s_waitcnt vmcnt(0)
	v_and_b32_e32 v84, 15, v54
	v_lshl_add_u64 v[60:61], s[22:23], 0, v[32:33]
	v_lshlrev_b32_e32 v32, 4, v57
	v_lshlrev_b32_e32 v2, 3, v55
	v_mov_b32_e32 v3, v33
	v_add_u32_e32 v8, 0, v0
	s_waitcnt lgkmcnt(0)
	v_lshl_add_u64 v[0:1], s[4:5], 0, v[32:33]
	s_lshl_b64 s[4:5], s[48:49], 12
	s_lshl_b32 s8, s8, 4
	v_lshl_add_u64 v[62:63], s[20:21], 0, v[2:3]
	v_lshlrev_b32_e32 v2, 8, v84
	v_and_b32_e32 v56, 31, v54
	s_or_b32 s4, s4, s8
	v_lshl_add_u64 v[2:3], s[16:17], 0, v[2:3]
	v_lshrrev_b32_e32 v4, 1, v54
	v_and_b32_e32 v6, 48, v54
	v_mov_b32_e32 v7, v33
	s_movk_i32 s8, 0x110
	v_lshlrev_b32_e32 v58, 3, v57
	v_and_b32_e32 v4, 24, v4
	v_mov_b32_e32 v5, v33
	v_lshl_add_u64 v[64:65], v[2:3], 0, v[6:7]
	v_lshl_add_u64 v[66:67], s[10:11], 0, v[6:7]
	v_mad_u32_u24 v7, v56, s8, v8
	v_add_u32_e32 v6, v8, v6
	v_mul_u32_u24_e32 v9, 0x110, v84
	v_lshlrev_b32_e32 v2, 5, v56
	v_mov_b32_e32 v3, v33
	v_lshlrev_b32_e32 v85, 1, v59
	v_add_u32_e32 v86, s44, v4
	v_lshl_add_u64 v[68:69], v[0:1], 0, v[2:3]
	v_lshl_add_u64 v[70:71], s[18:19], 0, v[32:33]
	v_lshl_add_u32 v32, v55, 1, v8
	v_lshl_add_u64 v[72:73], s[18:19], 0, v[4:5]
	s_mov_b32 s38, 0
	s_mov_b64 s[70:71], -1
	v_add_u32_e32 v87, v7, v58
	v_add_u32_e32 v88, v6, v9
.LBB0_332:
	v_or_b32_e32 v0, s38, v85
	v_ashrrev_i32_e32 v1, 31, v0
	v_lshl_add_u64 v[2:3], s[28:29], 0, v[0:1]
	v_lshlrev_b64 v[4:5], 10, v[2:3]
	v_lshl_add_u64 v[4:5], v[60:61], 0, v[4:5]
	global_load_dwordx2 v[74:75], v[4:5], off
	v_lshlrev_b64 v[4:5], 12, v[2:3]
	v_lshl_add_u64 v[6:7], v[68:69], 0, v[4:5]
	global_load_dwordx4 v[16:19], v[6:7], off
	global_load_dwordx4 v[20:23], v[6:7], off offset:1024
	global_load_dwordx4 v[24:27], v[6:7], off offset:2048
	global_load_dwordx4 v[28:31], v[6:7], off offset:3072
	v_lshl_add_u64 v[6:7], s[4:5], 0, v[0:1]
	v_lshlrev_b64 v[6:7], 9, v[6:7]
	v_lshl_add_u64 v[6:7], v[62:63], 0, v[6:7]
	v_lshl_add_u64 v[4:5], v[64:65], 0, v[4:5]
	global_load_dwordx2 v[82:83], v[6:7], off sc1
	global_load_dwordx4 v[34:37], v[4:5], off
	global_load_dwordx4 v[38:41], v[4:5], off offset:64
	global_load_dwordx4 v[42:45], v[4:5], off offset:128
	global_load_dwordx4 v[46:49], v[4:5], off offset:192
	v_lshlrev_b64 v[2:3], 6, v[2:3]
	v_lshl_add_u64 v[2:3], v[66:67], 0, v[2:3]
	global_load_dwordx4 v[50:53], v[2:3], off
	v_lshlrev_b32_e32 v2, 4, v0
	v_ashrrev_i32_e32 v3, 31, v2
	v_lshl_add_u32 v89, v0, 5, v86
	v_lshlrev_b64 v[0:1], 1, v[2:3]
	s_xor_b64 s[10:11], s[70:71], -1
	s_mov_b64 s[72:73], -1
	v_lshl_add_u64 v[76:77], v[70:71], 0, v[0:1]
	v_lshl_add_u64 v[78:79], v[72:73], 0, v[0:1]
	s_mov_b32 s38, 0
	v_mov_b32_e32 v100, 0
	v_mov_b32_e32 v101, 0
	v_mov_b32_e32 v102, 0
	v_mov_b32_e32 v103, 0
	v_mov_b32_e32 v104, 0
	v_mov_b32_e32 v105, 0
	v_mov_b32_e32 v106, 0
	v_mov_b32_e32 v107, 0
	v_mov_b32_e32 v108, 0
	v_mov_b32_e32 v109, 0
	v_mov_b32_e32 v110, 0
	v_mov_b32_e32 v111, 0
	v_mov_b32_e32 v112, 0
	v_mov_b32_e32 v113, 0
	v_mov_b32_e32 v114, 0
	v_mov_b32_e32 v115, 0
	s_waitcnt vmcnt(10)
	v_mov_b32_e32 v80, v74
	v_mov_b32_e32 v81, v74
	v_mov_b32_e32 v74, v75

; #define MFMA16(a, b, c) __builtin_amdgcn_mfma_f32_16x16x32_bf16((a), (b), (c), 0, 0, 0)
; DI unsigned pk2(float a, float b) { f2_t v = {a, b}; bf2_t r = __builtin_convertvector(v, bf2_t); return __builtin_bit_cast(unsigned, r); }
; DI float bflo(unsigned u) { return __uint_as_float(u << 16); }
; DI void ssm_out_item(const CP& p, int l, int item, char* smem) {
;     ...
;       for (int s2 = 0; s2 < 32; ++s2) {
;         const fl2 bu = {__uint_as_float((unsigned)sX[s2 * 136 + lane] << 16), __uint_as_float((unsigned)sX[s2 * 136 + 64 + lane] << 16)};
;         const fl2 xs = {-x.y, x.x};
;         x = x * a_r + xs * a_i + bu;
;         const unsigned pkx = pk2(x.x, x.y);
;         sX[s2 * 136 + lane] = (u16)(pkx & 0xffffu);
;         sX[s2 * 136 + 64 + lane] = (u16)(pkx >> 16);
;       }
;       __syncthreads();
;       f32x4v ya[2];
; #pragma unroll
;       for (int nb = 0; nb < 2; ++nb) {
;         ya[nb] = (f32x4v){0.f, 0.f, 0.f, 0.f};
; #pragma unroll
;         for (int ks = 0; ks < 4; ++ks) {
;           bf16x8 xb = *(const bf16x8*)(sX + (nb * 16 + l16) * 136 + ks * 32 + q4 * 8);
;           ya[nb] = MFMA16(cf[ks], xb, ya[nb]);
;         }
;       }
; #pragma unroll
;       for (int nb = 0; nb < 2; ++nb) {
;         const int s = sub * 32 + nb * 16 + l16;
;         const u32x2 uu = *(const u32x2*)(p.R + (tok0 + s) * TMW + 1408 + g * 16 + q4 * 4);
;         const float y0 = gelu_tanh(ya[nb][0] + dsk.x * bflo(uu.x));
.LBB0_334:
	v_add_u32_e32 v6, s39, v32
	ds_read_u16_d16_hi v100, v6
	ds_read_u16_d16_hi v101, v6 offset:128
	ds_read_u16_d16_hi v102, v6 offset:272
	ds_read_u16_d16_hi v103, v6 offset:400
	ds_read_u16_d16_hi v104, v6 offset:544
	ds_read_u16_d16_hi v105, v6 offset:672
	ds_read_u16_d16_hi v106, v6 offset:816
	ds_read_u16_d16_hi v107, v6 offset:944
	s_addk_i32 s39, 0x880
	v_mul_f32_e64 v2, v74, -v83
	v_mul_f32_e32 v3, v75, v82
	s_waitcnt lgkmcnt(6)
	v_fma_f32 v2, v80, v82, v2
	v_fma_f32 v3, v81, v83, v3
	v_add_f32_e32 v0, v2, v100
	v_add_f32_e32 v1, v3, v101
	v_cvt_pk_bf16_f32 v2, v0, v1
	ds_write_b16 v6, v2
	ds_write_b16_d16_hi v6, v2 offset:128
	v_mul_f32_e64 v4, v74, -v1
	v_mul_f32_e32 v5, v75, v0
	s_waitcnt lgkmcnt(6)
	v_fma_f32 v0, v80, v0, v4
	v_fma_f32 v1, v81, v1, v5
	v_add_f32_e32 v0, v0, v102
	v_add_f32_e32 v1, v1, v103
	v_cvt_pk_bf16_f32 v2, v0, v1
	ds_write_b16 v6, v2 offset:272
	ds_write_b16_d16_hi v6, v2 offset:400
	v_mul_f32_e64 v4, v74, -v1
	v_mul_f32_e32 v5, v75, v0
	s_waitcnt lgkmcnt(6)
	v_fma_f32 v0, v80, v0, v4
	v_fma_f32 v1, v81, v1, v5
	v_add_f32_e32 v0, v0, v104
	v_add_f32_e32 v1, v1, v105
	v_cvt_pk_bf16_f32 v2, v0, v1
	ds_write_b16 v6, v2 offset:544
	ds_write_b16_d16_hi v6, v2 offset:672
	v_mul_f32_e64 v4, v74, -v1
	v_mul_f32_e32 v5, v75, v0
	s_waitcnt lgkmcnt(6)
	v_fma_f32 v0, v80, v0, v4
	v_fma_f32 v1, v81, v1, v5
	v_add_f32_e32 v0, v0, v106
	v_add_f32_e32 v1, v1, v107
	v_cvt_pk_bf16_f32 v2, v0, v1
	ds_write_b16 v6, v2 offset:816
	ds_write_b16_d16_hi v6, v2 offset:944
	ds_read_u16_d16_hi v108, v6 offset:1088
	ds_read_u16_d16_hi v109, v6 offset:1216
	ds_read_u16_d16_hi v110, v6 offset:1360
	ds_read_u16_d16_hi v111, v6 offset:1488
	ds_read_u16_d16_hi v112, v6 offset:1632
	ds_read_u16_d16_hi v113, v6 offset:1760
	ds_read_u16_d16_hi v114, v6 offset:1904
	ds_read_u16_d16_hi v115, v6 offset:2032
	v_mul_f32_e64 v4, v74, -v1
	v_mul_f32_e32 v5, v75, v0
	s_waitcnt lgkmcnt(6)
	v_fma_f32 v0, v80, v0, v4
	v_fma_f32 v1, v81, v1, v5
	v_add_f32_e32 v0, v0, v108
	v_add_f32_e32 v1, v1, v109
	v_cvt_pk_bf16_f32 v2, v0, v1
	ds_write_b16 v6, v2 offset:1088
	ds_write_b16_d16_hi v6, v2 offset:1216
	v_mul_f32_e64 v4, v74, -v1
	v_mul_f32_e32 v5, v75, v0
	s_waitcnt lgkmcnt(6)
	v_fma_f32 v0, v80, v0, v4
	v_fma_f32 v1, v81, v1, v5
	v_add_f32_e32 v0, v0, v110
	v_add_f32_e32 v1, v1, v111
	v_cvt_pk_bf16_f32 v2, v0, v1
	ds_write_b16 v6, v2 offset:1360
	ds_write_b16_d16_hi v6, v2 offset:1488
	v_mul_f32_e64 v4, v74, -v1
	v_mul_f32_e32 v5, v75, v0
	s_waitcnt lgkmcnt(6)
	v_fma_f32 v0, v80, v0, v4
	v_fma_f32 v1, v81, v1, v5
	v_add_f32_e32 v0, v0, v112
	v_add_f32_e32 v1, v1, v113
	v_cvt_pk_bf16_f32 v2, v0, v1
	ds_write_b16 v6, v2 offset:1632
	ds_write_b16_d16_hi v6, v2 offset:1760
	v_mul_f32_e64 v4, v74, -v1
	v_mul_f32_e32 v5, v75, v0
	s_waitcnt lgkmcnt(6)
	v_fma_f32 v0, v80, v0, v4
	v_fma_f32 v1, v81, v1, v5
	v_add_f32_e32 v82, v0, v114
	v_add_f32_e32 v83, v1, v115
	v_cvt_pk_bf16_f32 v0, v82, v83
	ds_write_b16 v6, v0 offset:1904
	ds_write_b16_d16_hi v6, v0 offset:2032
	s_cmpk_eq_i32 s39, 0x2200
	s_cbranch_scc0 .LBB0_334
	s_waitcnt lgkmcnt(0)
	s_barrier
	ds_read_b128 v[0:3], v88
	ds_read_b128 v[4:7], v88 offset:64
	s_waitcnt lgkmcnt(1)
	v_mfma_f32_16x16x32_bf16 v[0:3], v[34:37], v[0:3], 0
	ds_read_b128 v[10:13], v88 offset:4416
	s_mov_b64 s[72:73], 0
	s_waitcnt lgkmcnt(1)
	v_mfma_f32_16x16x32_bf16 v[0:3], v[38:41], v[4:7], v[0:3]
	ds_read_b128 v[4:7], v88 offset:128
	s_waitcnt lgkmcnt(0)
	v_mfma_f32_16x16x32_bf16 v[0:3], v[42:45], v[4:7], v[0:3]
	ds_read_b128 v[4:7], v88 offset:192
	s_waitcnt lgkmcnt(0)
	v_mfma_f32_16x16x32_bf16 v[6:9], v[46:49], v[4:7], v[0:3]
	v_or_b32_e32 v5, s38, v84
	s_nop 3
	ds_read_b128 v[0:3], v88 offset:4352
	v_or_b32_e32 v4, s6, v5
	s_waitcnt lgkmcnt(0)
	v_mfma_f32_16x16x32_bf16 v[0:3], v[34:37], v[0:3], 0
	v_mfma_f32_16x16x32_bf16 v[0:3], v[38:41], v[10:13], v[0:3]
	ds_read_b128 v[10:13], v88 offset:4480
	s_waitcnt lgkmcnt(0)
	v_mfma_f32_16x16x32_bf16 v[0:3], v[42:45], v[10:13], v[0:3]
	ds_read_b128 v[10:13], v88 offset:4544
	s_waitcnt lgkmcnt(0)
	v_mfma_f32_16x16x32_bf16 v[0:3], v[46:49], v[10:13], v[0:3]
	v_mad_u64_u32 v[10:11], s[38:39], v4, s45, v[78:79]
	v_mad_u32_u24 v11, s7, v212, v11
	global_load_dwordx2 v[10:11], v[10:11], off offset:2816
	v_or_b32_e32 v4, 16, v4
	s_waitcnt vmcnt(0)
; DI unsigned pk2(float a, float b) { f2_t v = {a, b}; bf2_t r = __builtin_convertvector(v, bf2_t); return __builtin_bit_cast(unsigned, r); }
; DI float bflo(unsigned u) { return __uint_as_float(u << 16); }
; DI float bfhi(unsigned u) { return __uint_as_float(u & 0xffff0000u); }
; DI void ssm_out_item(const CP& p, int l, int item, char* smem) {
;     ...
; #pragma unroll
;       for (int nb = 0; nb < 2; ++nb) {
;         const int s = sub * 32 + nb * 16 + l16;
;         const u32x2 uu = *(const u32x2*)(p.R + (tok0 + s) * TMW + 1408 + g * 16 + q4 * 4);
;         const float y0 = gelu_tanh(ya[nb][0] + dsk.x * bflo(uu.x));
;         const float y1 = gelu_tanh(ya[nb][1] + dsk.y * bfhi(uu.x));
;         const float y2 = gelu_tanh(ya[nb][2] + dsk.z * bflo(uu.y));
;         const float y3 = gelu_tanh(ya[nb][3] + dsk.w * bfhi(uu.y));
;         u32x2 v;
;         v.x = pk2(y0, y1); v.y = pk2(y2, y3);
;         *(u32x2*)(sY + s * 264 + g * 16 + q4 * 4) = v;
;       }
	v_lshlrev_b32_e32 v12, 16, v10
	v_and_b32_e32 v13, 0xffff0000, v10
	v_pk_fma_f32 v[6:7], v[50:51], v[12:13], v[6:7]
	s_nop 0
	v_mul_f32_e32 v10, 0x3d372713, v6
	v_mul_f32_e32 v10, v6, v10
	v_fma_f32 v10, v6, v10, v6
	v_mul_f32_e32 v10, 0x3f4c422a, v10
	v_add_f32_e32 v10, v10, v10
	v_mul_f32_e32 v10, 0x3fb8aa3b, v10
	v_exp_f32_e32 v12, v10
	v_mul_f32_e32 v10, 0x3d372713, v7
	v_mul_f32_e32 v10, v7, v10
	v_fma_f32 v10, v7, v10, v7
	v_mul_f32_e32 v10, 0x3f4c422a, v10
	v_add_f32_e32 v10, v10, v10
	v_mul_f32_e32 v10, 0x3fb8aa3b, v10
	v_exp_f32_e32 v13, v10
	v_pk_mul_f32 v[6:7], v[6:7], 0.5 op_sel_hi:[1,0]
	v_pk_add_f32 v[12:13], v[12:13], 1.0 op_sel_hi:[1,0]
	s_nop 0
	v_div_scale_f32 v10, s[38:39], v13, v13, 2.0
	v_rcp_f32_e32 v14, v10
	s_nop 0
	v_fma_f32 v15, -v10, v14, 1.0
	v_fmac_f32_e32 v14, v15, v14
	v_div_scale_f32 v15, vcc, 2.0, v13, 2.0
	v_mul_f32_e32 v90, v15, v14
	v_fma_f32 v91, -v10, v90, v15
	v_fmac_f32_e32 v90, v91, v14
	v_fma_f32 v10, -v10, v90, v15
	v_div_fmas_f32 v10, v10, v14, v90
	v_div_fixup_f32 v13, v10, v13, 2.0
	v_div_scale_f32 v10, s[38:39], v12, v12, 2.0
	v_rcp_f32_e32 v14, v10
	s_nop 0
	v_fma_f32 v15, -v10, v14, 1.0
	v_fmac_f32_e32 v14, v15, v14
	v_div_scale_f32 v15, vcc, 2.0, v12, 2.0
	v_mul_f32_e32 v90, v15, v14
	v_fma_f32 v91, -v10, v90, v15
	v_fmac_f32_e32 v90, v91, v14
	v_fma_f32 v10, -v10, v90, v15
	v_div_fmas_f32 v10, v10, v14, v90
	v_div_fixup_f32 v12, v10, v12, 2.0
	v_lshlrev_b32_e32 v10, 16, v11
	v_and_b32_e32 v11, 0xffff0000, v11
	v_pk_fma_f32 v[8:9], v[52:53], v[10:11], v[8:9]
	v_pk_add_f32 v[12:13], v[12:13], 1.0 op_sel_hi:[1,0] neg_lo:[1,0] neg_hi:[1,0]
	v_mul_f32_e32 v10, 0x3d372713, v8
	v_mul_f32_e32 v11, 0x3d372713, v9
	v_mul_f32_e32 v10, v8, v10
	v_mul_f32_e32 v11, v9, v11
	v_fma_f32 v10, v8, v10, v8
	v_fma_f32 v11, v9, v11, v9
	v_mul_f32_e32 v10, 0x3f4c422a, v10
	v_mul_f32_e32 v11, 0x3f4c422a, v11
	v_add_f32_e32 v10, v10, v10
	v_add_f32_e32 v11, v11, v11
	v_mul_f32_e32 v10, 0x3fb8aa3b, v10
	v_mul_f32_e32 v11, 0x3fb8aa3b, v11
	v_exp_f32_e32 v10, v10
	v_exp_f32_e32 v11, v11
	v_pk_add_f32 v[12:13], v[12:13], 1.0 op_sel_hi:[1,0]
	v_pk_mul_f32 v[8:9], v[8:9], 0.5 op_sel_hi:[1,0]
	v_pk_mul_f32 v[6:7], v[6:7], v[12:13]
	v_pk_add_f32 v[10:11], v[10:11], 1.0 op_sel_hi:[1,0]
	s_nop 0
	v_div_scale_f32 v12, s[38:39], v11, v11, 2.0
	v_rcp_f32_e32 v13, v12
	s_nop 0
	v_fma_f32 v14, -v12, v13, 1.0
	v_fmac_f32_e32 v13, v14, v13
	v_div_scale_f32 v14, vcc, 2.0, v11, 2.0
	v_mul_f32_e32 v15, v14, v13
	v_fma_f32 v90, -v12, v15, v14
	v_fmac_f32_e32 v15, v90, v13
	v_fma_f32 v12, -v12, v15, v14
	v_div_fmas_f32 v12, v12, v13, v15
	v_div_fixup_f32 v11, v12, v11, 2.0
	v_div_scale_f32 v12, s[38:39], v10, v10, 2.0
	v_rcp_f32_e32 v13, v12
	s_nop 0
	v_fma_f32 v14, -v12, v13, 1.0
	v_fmac_f32_e32 v13, v14, v13
	v_div_scale_f32 v14, vcc, 2.0, v10, 2.0
	v_mul_f32_e32 v15, v14, v13
	v_fma_f32 v90, -v12, v15, v14
	v_fmac_f32_e32 v15, v90, v13
	v_fma_f32 v12, -v12, v15, v14
	v_div_fmas_f32 v12, v12, v13, v15
	v_div_fixup_f32 v10, v12, v10, 2.0
	v_pk_add_f32 v[10:11], v[10:11], 1.0 op_sel_hi:[1,0] neg_lo:[1,0] neg_hi:[1,0]
	s_nop 0
	v_pk_add_f32 v[10:11], v[10:11], 1.0 op_sel_hi:[1,0]
	s_nop 0
	v_pk_mul_f32 v[8:9], v[8:9], v[10:11]
	v_cvt_pk_bf16_f32 v10, v6, v7
	v_mad_u32_u24 v6, v5, s88, v89
	v_mad_u64_u32 v[4:5], s[38:39], v4, s45, v[78:79]
	v_mad_u32_u24 v5, s7, v212, v5
	global_load_dwordx2 v[4:5], v[4:5], off offset:2816
	v_cvt_pk_bf16_f32 v11, v8, v9
	ds_write_b64 v6, v[10:11]
	s_waitcnt vmcnt(0)
	v_lshlrev_b32_e32 v8, 16, v4
	v_and_b32_e32 v9, 0xffff0000, v4
	v_pk_fma_f32 v[0:1], v[50:51], v[8:9], v[0:1]
	s_nop 0
	v_mul_f32_e32 v4, 0x3d372713, v0
	v_mul_f32_e32 v4, v0, v4
	v_fma_f32 v4, v0, v4, v0
	v_mul_f32_e32 v4, 0x3f4c422a, v4
	v_add_f32_e32 v4, v4, v4
	v_mul_f32_e32 v4, 0x3fb8aa3b, v4
	v_exp_f32_e32 v8, v4
	v_mul_f32_e32 v4, 0x3d372713, v1
	v_mul_f32_e32 v4, v1, v4
	v_fma_f32 v4, v1, v4, v1
	v_mul_f32_e32 v4, 0x3f4c422a, v4
	v_add_f32_e32 v4, v4, v4
	v_mul_f32_e32 v4, 0x3fb8aa3b, v4
	v_exp_f32_e32 v9, v4
	v_pk_mul_f32 v[0:1], v[0:1], 0.5 op_sel_hi:[1,0]
	v_pk_add_f32 v[8:9], v[8:9], 1.0 op_sel_hi:[1,0]
	s_nop 0
	v_div_scale_f32 v4, s[38:39], v9, v9, 2.0
	v_rcp_f32_e32 v7, v4
	s_nop 0
	v_fma_f32 v10, -v4, v7, 1.0
	v_fmac_f32_e32 v7, v10, v7
	v_div_scale_f32 v10, vcc, 2.0, v9, 2.0
	v_mul_f32_e32 v11, v10, v7
	v_fma_f32 v12, -v4, v11, v10
	v_fmac_f32_e32 v11, v12, v7
	v_fma_f32 v4, -v4, v11, v10
	v_div_fmas_f32 v4, v4, v7, v11
	v_div_fixup_f32 v9, v4, v9, 2.0
	v_div_scale_f32 v4, s[38:39], v8, v8, 2.0
	v_rcp_f32_e32 v7, v4
	s_nop 0
	v_fma_f32 v10, -v4, v7, 1.0
	v_fmac_f32_e32 v7, v10, v7
	v_div_scale_f32 v10, vcc, 2.0, v8, 2.0
	v_mul_f32_e32 v11, v10, v7
	v_fma_f32 v12, -v4, v11, v10
	v_fmac_f32_e32 v11, v12, v7
	v_fma_f32 v4, -v4, v11, v10
	v_div_fmas_f32 v4, v4, v7, v11
	v_div_fixup_f32 v8, v4, v8, 2.0
	v_lshlrev_b32_e32 v4, 16, v5
	v_and_b32_e32 v5, 0xffff0000, v5
	v_pk_fma_f32 v[2:3], v[52:53], v[4:5], v[2:3]
	v_pk_add_f32 v[8:9], v[8:9], 1.0 op_sel_hi:[1,0] neg_lo:[1,0] neg_hi:[1,0]
	v_mul_f32_e32 v4, 0x3d372713, v2
	v_mul_f32_e32 v5, 0x3d372713, v3
	v_mul_f32_e32 v4, v2, v4
	v_mul_f32_e32 v5, v3, v5
	v_fma_f32 v4, v2, v4, v2
	v_fma_f32 v5, v3, v5, v3
	v_mul_f32_e32 v4, 0x3f4c422a, v4
	v_mul_f32_e32 v5, 0x3f4c422a, v5
	v_add_f32_e32 v4, v4, v4
	v_add_f32_e32 v5, v5, v5
	v_mul_f32_e32 v4, 0x3fb8aa3b, v4
	v_mul_f32_e32 v5, 0x3fb8aa3b, v5
	v_exp_f32_e32 v4, v4
	v_exp_f32_e32 v5, v5
	v_pk_add_f32 v[8:9], v[8:9], 1.0 op_sel_hi:[1,0]
	v_pk_mul_f32 v[2:3], v[2:3], 0.5 op_sel_hi:[1,0]
	v_pk_mul_f32 v[0:1], v[0:1], v[8:9]
	v_pk_add_f32 v[4:5], v[4:5], 1.0 op_sel_hi:[1,0]
	v_cvt_pk_bf16_f32 v0, v0, v1
	v_div_scale_f32 v7, s[38:39], v5, v5, 2.0
	v_rcp_f32_e32 v8, v7
	s_nop 0
	v_fma_f32 v9, -v7, v8, 1.0
	v_fmac_f32_e32 v8, v9, v8
	v_div_scale_f32 v9, vcc, 2.0, v5, 2.0
	v_mul_f32_e32 v10, v9, v8
	v_fma_f32 v11, -v7, v10, v9
	v_fmac_f32_e32 v10, v11, v8
	v_fma_f32 v7, -v7, v10, v9
	v_div_fmas_f32 v7, v7, v8, v10
	v_div_fixup_f32 v5, v7, v5, 2.0
	v_div_scale_f32 v7, s[38:39], v4, v4, 2.0
	v_rcp_f32_e32 v8, v7
	s_mov_b32 s38, 32
	v_fma_f32 v9, -v7, v8, 1.0
	v_fmac_f32_e32 v8, v9, v8
	v_div_scale_f32 v9, vcc, 2.0, v4, 2.0
	v_mul_f32_e32 v10, v9, v8
	v_fma_f32 v11, -v7, v10, v9
	v_fmac_f32_e32 v10, v11, v8
	v_fma_f32 v7, -v7, v10, v9
	v_div_fmas_f32 v7, v7, v8, v10
	v_div_fixup_f32 v4, v7, v4, 2.0
	v_pk_add_f32 v[4:5], v[4:5], 1.0 op_sel_hi:[1,0] neg_lo:[1,0] neg_hi:[1,0]
	s_and_b64 vcc, exec, s[70:71]
	v_pk_add_f32 v[4:5], v[4:5], 1.0 op_sel_hi:[1,0]
	s_nop 0
	v_pk_mul_f32 v[2:3], v[2:3], v[4:5]
	s_nop 0
	v_cvt_pk_bf16_f32 v1, v2, v3
	ds_write_b64 v6, v[0:1] offset:8448
	s_waitcnt lgkmcnt(0)
	s_barrier
; DI void ssm_out_item(const CP& p, int l, int item, char* smem) {
;     ...
;       __builtin_amdgcn_wave_barrier();
; #pragma unroll 8
;       for (int s2 = 0; s2 < 32; ++s2) {
;         const fl2 bu = {__uint_as_float((unsigned)sX[s2 * 136 + lane] << 16), __uint_as_float((unsigned)sX[s2 * 136 + 64 + lane] << 16)};
;         const fl2 xs = {-x.y, x.x};
;         x = x * a_r + xs * a_i + bu;
;         const unsigned pkx = pk2(x.x, x.y);
;         sX[s2 * 136 + lane] = (u16)(pkx & 0xffffu);
;         sX[s2 * 136 + 64 + lane] = (u16)(pkx >> 16);
;       }
;       __syncthreads();
;       f32x4v ya[2];
; #pragma unroll
;       for (int nb = 0; nb < 2; ++nb) {
;         ya[nb] = (f32x4v){0.f, 0.f, 0.f, 0.f};
; #pragma unroll
;         for (int ks = 0; ks < 4; ++ks) {
;           bf16x8 xb = *(const bf16x8*)(sX + (nb * 16 + l16) * 136 + ks * 32 + q4 * 8);
;           ya[nb] = MFMA16(cf[ks], xb, ya[nb]);
;         }
;       }
; #pragma unroll
;       for (int nb = 0; nb < 2; ++nb) {
;         const int s = sub * 32 + nb * 16 + l16;
;         const u32x2 uu = *(const u32x2*)(p.R + (tok0 + s) * TMW + 1408 + g * 16 + q4 * 4);
;         const float y0 = gelu_tanh(ya[nb][0] + dsk.x * bflo(uu.x));
;         const float y1 = gelu_tanh(ya[nb][1] + dsk.y * bfhi(uu.x));
;         const float y2 = gelu_tanh(ya[nb][2] + dsk.z * bflo(uu.y));
;         const float y3 = gelu_tanh(ya[nb][3] + dsk.w * bfhi(uu.y));
;         u32x2 v;
;         v.x = pk2(y0, y1); v.y = pk2(y2, y3);
;         *(u32x2*)(sY + s * 264 + g * 16 + q4 * 4) = v;
;       }
;       __syncthreads();
;     }
;   }
;   __syncthreads();
;   f32x16 acc[2];
; #pragma unroll
;   for (int j = 0; j < 2; ++j)
; #pragma unroll
;     for (int r = 0; r < 16; ++r) acc[j][r] = 0.f;
;   const u16* wg = p.wt_glu + (size_t)l * 65536;
; #pragma unroll
;   for (int ks = 0; ks < 16; ++ks) {
;     bf16x8 fa, fb[2];
;     fa = *(const bf16x8*)(wg + (size_t)(w * 32 + l32) * 256 + ks * 16 + hh * 8);
; #pragma unroll
;     for (int i = 0; i < 2; ++i) fb[i] = *(const bf16x8*)(sY + (i * 32 + l32) * 264 + ks * 16 + hh * 8);
; #pragma unroll
;     for (int j = 0; j < 2; ++j) acc[j] = MFMA32(fa, fb[j], acc[j]);
;   }
;   const float* bg = p.b_glu + (size_t)l * 256;
; #pragma unroll
;   for (int j = 0; j < 2; ++j) {
;     const int token = j * 32 + l32;
;     float sq = 0.f;
; #pragma unroll
;     for (int blk = 0; blk < 4; ++blk) {
	s_cbranch_vccz .LBB0_333
	s_mov_b32 s38, 1
	s_mov_b64 s[70:71], 0
	s_and_b64 vcc, exec, s[10:11]
	s_cbranch_vccz .LBB0_332
	v_lshlrev_b32_e32 v37, 5, v59
	v_or_b32_e32 v0, v37, v56
	v_ashrrev_i32_e32 v1, 31, v0
	v_lshlrev_b64 v[0:1], 9, v[0:1]
	v_lshl_add_u64 v[0:1], s[30:31], 0, v[0:1]
	v_lshlrev_b32_e32 v32, 1, v58
	v_lshl_add_u64 v[34:35], v[0:1], 0, v[32:33]
	s_barrier
	global_load_dwordx4 v[100:103], v[34:35], off
	global_load_dwordx4 v[104:107], v[34:35], off offset:32
	global_load_dwordx4 v[108:111], v[34:35], off offset:64
	global_load_dwordx4 v[112:115], v[34:35], off offset:96
	global_load_dwordx4 v[116:119], v[34:35], off offset:128
	global_load_dwordx4 v[120:123], v[34:35], off offset:160
	global_load_dwordx4 v[124:127], v[34:35], off offset:192
	global_load_dwordx4 v[128:131], v[34:35], off offset:224
	global_load_dwordx4 v[132:135], v[34:35], off offset:256
	global_load_dwordx4 v[136:139], v[34:35], off offset:288
	global_load_dwordx4 v[140:143], v[34:35], off offset:320
	global_load_dwordx4 v[144:147], v[34:35], off offset:352
	global_load_dwordx4 v[148:151], v[34:35], off offset:384
	global_load_dwordx4 v[168:171], v[34:35], off offset:416
	global_load_dwordx4 v[172:175], v[34:35], off offset:448
	global_load_dwordx4 v[176:179], v[34:35], off offset:480
	v_add_u32_e32 v4, s44, v32
	v_mad_u32_u24 v50, v56, s88, v4
	v_mad_u32_u24 v32, v56, s88, v213
	v_add_u32_e32 v51, v4, v32
	v_mul_u32_u24_e32 v36, 0x210, v56
	v_cmp_gt_u32_e64 s[4:5], 32, v55
	ds_read_b128 v[180:183], v50
	ds_read_b128 v[184:187], v51
	ds_read_b128 v[188:191], v50 offset:32
	ds_read_b128 v[192:195], v51 offset:32
	s_waitcnt vmcnt(15) lgkmcnt(2)
	v_mfma_f32_32x32x16_bf16 v[16:31], v[100:103], v[180:183], 0
	v_mfma_f32_32x32x16_bf16 v[0:15], v[100:103], v[184:187], 0
	ds_read_b128 v[180:183], v50 offset:64
	ds_read_b128 v[184:187], v51 offset:64
	s_waitcnt vmcnt(14) lgkmcnt(2)
	v_mfma_f32_32x32x16_bf16 v[16:31], v[104:107], v[188:191], v[16:31]
	v_mfma_f32_32x32x16_bf16 v[0:15], v[104:107], v[192:195], v[0:15]
	ds_read_b128 v[188:191], v50 offset:96
	ds_read_b128 v[192:195], v51 offset:96
	s_waitcnt vmcnt(13) lgkmcnt(2)
	v_mfma_f32_32x32x16_bf16 v[16:31], v[108:111], v[180:183], v[16:31]
	v_mfma_f32_32x32x16_bf16 v[0:15], v[108:111], v[184:187], v[0:15]
	ds_read_b128 v[180:183], v50 offset:128
	ds_read_b128 v[184:187], v51 offset:128
	s_waitcnt vmcnt(12) lgkmcnt(2)
	v_mfma_f32_32x32x16_bf16 v[16:31], v[112:115], v[188:191], v[16:31]
	v_mfma_f32_32x32x16_bf16 v[0:15], v[112:115], v[192:195], v[0:15]
	ds_read_b128 v[188:191], v50 offset:160
	ds_read_b128 v[192:195], v51 offset:160
	s_waitcnt vmcnt(11) lgkmcnt(2)
	v_mfma_f32_32x32x16_bf16 v[16:31], v[116:119], v[180:183], v[16:31]
	v_mfma_f32_32x32x16_bf16 v[0:15], v[116:119], v[184:187], v[0:15]
	ds_read_b128 v[180:183], v50 offset:192
	ds_read_b128 v[184:187], v51 offset:192
	s_waitcnt vmcnt(10) lgkmcnt(2)
	v_mfma_f32_32x32x16_bf16 v[16:31], v[120:123], v[188:191], v[16:31]
	v_mfma_f32_32x32x16_bf16 v[0:15], v[120:123], v[192:195], v[0:15]
	ds_read_b128 v[188:191], v50 offset:224
	ds_read_b128 v[192:195], v51 offset:224
	s_waitcnt vmcnt(9) lgkmcnt(2)
	v_mfma_f32_32x32x16_bf16 v[16:31], v[124:127], v[180:183], v[16:31]
	v_mfma_f32_32x32x16_bf16 v[0:15], v[124:127], v[184:187], v[0:15]
	ds_read_b128 v[180:183], v50 offset:256
	ds_read_b128 v[184:187], v51 offset:256
	s_waitcnt vmcnt(8) lgkmcnt(2)
	v_mfma_f32_32x32x16_bf16 v[16:31], v[128:131], v[188:191], v[16:31]
	v_mfma_f32_32x32x16_bf16 v[0:15], v[128:131], v[192:195], v[0:15]
	ds_read_b128 v[188:191], v50 offset:288
	ds_read_b128 v[192:195], v51 offset:288
	s_waitcnt vmcnt(7) lgkmcnt(2)
	v_mfma_f32_32x32x16_bf16 v[16:31], v[132:135], v[180:183], v[16:31]
	v_mfma_f32_32x32x16_bf16 v[0:15], v[132:135], v[184:187], v[0:15]
	ds_read_b128 v[180:183], v50 offset:320
	ds_read_b128 v[184:187], v51 offset:320
	s_waitcnt vmcnt(6) lgkmcnt(2)
	v_mfma_f32_32x32x16_bf16 v[16:31], v[136:139], v[188:191], v[16:31]
	v_mfma_f32_32x32x16_bf16 v[0:15], v[136:139], v[192:195], v[0:15]
	ds_read_b128 v[188:191], v50 offset:352
	ds_read_b128 v[192:195], v51 offset:352
	s_waitcnt vmcnt(5) lgkmcnt(2)
	v_mfma_f32_32x32x16_bf16 v[16:31], v[140:143], v[180:183], v[16:31]
	v_mfma_f32_32x32x16_bf16 v[0:15], v[140:143], v[184:187], v[0:15]
	ds_read_b128 v[180:183], v50 offset:384
	ds_read_b128 v[184:187], v51 offset:384
	s_waitcnt vmcnt(4) lgkmcnt(2)
	v_mfma_f32_32x32x16_bf16 v[16:31], v[144:147], v[188:191], v[16:31]
	v_mfma_f32_32x32x16_bf16 v[0:15], v[144:147], v[192:195], v[0:15]
	ds_read_b128 v[188:191], v50 offset:416
	ds_read_b128 v[192:195], v51 offset:416
	s_waitcnt vmcnt(3) lgkmcnt(2)
	v_mfma_f32_32x32x16_bf16 v[16:31], v[148:151], v[180:183], v[16:31]
	v_mfma_f32_32x32x16_bf16 v[0:15], v[148:151], v[184:187], v[0:15]
	ds_read_b128 v[180:183], v50 offset:448
	ds_read_b128 v[184:187], v51 offset:448
	s_waitcnt vmcnt(2) lgkmcnt(2)
	v_mfma_f32_32x32x16_bf16 v[16:31], v[168:171], v[188:191], v[16:31]
	v_mfma_f32_32x32x16_bf16 v[0:15], v[168:171], v[192:195], v[0:15]
	ds_read_b128 v[188:191], v50 offset:480
	ds_read_b128 v[192:195], v51 offset:480
	s_waitcnt vmcnt(1) lgkmcnt(2)
	v_mfma_f32_32x32x16_bf16 v[16:31], v[172:175], v[180:183], v[16:31]
	v_mfma_f32_32x32x16_bf16 v[0:15], v[172:175], v[184:187], v[0:15]
	s_waitcnt vmcnt(0) lgkmcnt(0)
	v_mfma_f32_32x32x16_bf16 v[16:31], v[176:179], v[188:191], v[16:31]
	v_mfma_f32_32x32x16_bf16 v[0:15], v[176:179], v[192:195], v[0:15]
	v_and_b32_e32 v34, 0x3fffffc0, v54
	v_mov_b32_e32 v35, s7
	v_lshl_or_b32 v40, v57, 2, v37
	v_ashrrev_i32_e32 v41, 31, v40
	v_lshl_add_u64 v[38:39], v[40:41], 2, s[68:69]
	global_load_dwordx4 v[50:53], v[38:39], off
	v_lshl_add_u32 v48, v34, 2, s36
	v_or_b32_e32 v34, s6, v56
	v_lshlrev_b64 v[34:35], 11, v[34:35]
	v_lshl_add_u64 v[44:45], s[66:67], 0, v[34:35]
	v_lshlrev_b32_e32 v34, 1, v40
	v_add3_u32 v46, s44, v36, v34
	ds_read2_b64 v[34:37], v46 offset1:2
	v_lshl_add_u64 v[44:45], v[40:41], 1, v[44:45]
	s_waitcnt vmcnt(0)
; DI unsigned pk2(float a, float b) { f2_t v = {a, b}; bf2_t r = __builtin_convertvector(v, bf2_t); return __builtin_bit_cast(unsigned, r); }
; DI float bflo(unsigned u) { return __uint_as_float(u << 16); }
; DI float bfhi(unsigned u) { return __uint_as_float(u & 0xffff0000u); }
; DI void ssm_out_item(const CP& p, int l, int item, char* smem) {
;     ...
; #pragma unroll
;     for (int blk = 0; blk < 4; ++blk) {
;       const int ch = w * 32 + 8 * blk + 4 * hh;
;       const fl4 bv = *(const fl4*)(bg + ch);
;       const u32x2 yy = *(const u32x2*)(sY + token * 264 + ch);
;       const float g0 = 1.f / (1.f + __expf(-(acc[j][4 * blk] + bv.x)));
;       const float g1 = 1.f / (1.f + __expf(-(acc[j][4 * blk + 1] + bv.y)));
;       const float g2 = 1.f / (1.f + __expf(-(acc[j][4 * blk + 2] + bv.z)));
;       const float g3 = 1.f / (1.f + __expf(-(acc[j][4 * blk + 3] + bv.w)));
;       const float o0 = bflo(yy.x) * g0, o1 = bfhi(yy.x) * g1, o2 = bflo(yy.y) * g2, o3 = bfhi(yy.y) * g3;
;       sq += o0 * o0 + o1 * o1 + o2 * o2 + o3 * o3;
;       u32x2 v;
;       v.x = pk2(o0, o1); v.y = pk2(o2, o3);
;       *(u32x2*)(p.mixed + (tok0 + token) * 1024 + 768 + ch) = v;
;     }
	v_add_f32_e32 v16, v16, v50
	v_add_f32_e32 v17, v17, v51
	v_mul_f32_e32 v16, 0xbfb8aa3b, v16
	v_mul_f32_e32 v17, 0xbfb8aa3b, v17
	v_exp_f32_e32 v16, v16
	v_exp_f32_e32 v17, v17
	v_add_f32_e32 v18, v18, v52
	v_add_f32_e32 v19, v19, v53
	v_mul_f32_e32 v18, 0xbfb8aa3b, v18
	v_pk_add_f32 v[16:17], v[16:17], 1.0 op_sel_hi:[1,0]
	v_mul_f32_e32 v19, 0xbfb8aa3b, v19
	v_div_scale_f32 v42, s[10:11], v17, v17, 1.0
	v_rcp_f32_e32 v43, v42
	v_exp_f32_e32 v18, v18
	v_exp_f32_e32 v19, v19
	v_fma_f32 v47, -v42, v43, 1.0
	v_fmac_f32_e32 v43, v47, v43
	v_div_scale_f32 v47, vcc, 1.0, v17, 1.0
	v_mul_f32_e32 v49, v47, v43
	v_fma_f32 v50, -v42, v49, v47
	v_fmac_f32_e32 v49, v50, v43
	v_fma_f32 v42, -v42, v49, v47
	v_div_fmas_f32 v42, v42, v43, v49
	v_div_fixup_f32 v17, v42, v17, 1.0
	v_div_scale_f32 v42, s[10:11], v16, v16, 1.0
	v_rcp_f32_e32 v43, v42
	v_pk_add_f32 v[18:19], v[18:19], 1.0 op_sel_hi:[1,0]
	v_fma_f32 v47, -v42, v43, 1.0
	v_fmac_f32_e32 v43, v47, v43
	v_div_scale_f32 v47, vcc, 1.0, v16, 1.0
	v_mul_f32_e32 v49, v47, v43
	v_fma_f32 v50, -v42, v49, v47
	v_fmac_f32_e32 v49, v50, v43
	v_fma_f32 v42, -v42, v49, v47
	v_div_fmas_f32 v42, v42, v43, v49
	v_div_fixup_f32 v16, v42, v16, 1.0
	s_waitcnt lgkmcnt(0)
	v_lshlrev_b32_e32 v42, 16, v34
	v_and_b32_e32 v43, 0xffff0000, v34
	v_div_scale_f32 v34, s[10:11], v19, v19, 1.0
	v_pk_mul_f32 v[16:17], v[16:17], v[42:43]
	v_rcp_f32_e32 v42, v34
	s_nop 0
	v_fma_f32 v43, -v34, v42, 1.0
	v_fmac_f32_e32 v42, v43, v42
	v_div_scale_f32 v43, vcc, 1.0, v19, 1.0
	v_mul_f32_e32 v47, v43, v42
	v_fma_f32 v49, -v34, v47, v43
	v_fmac_f32_e32 v47, v49, v42
	v_fma_f32 v34, -v34, v47, v43
	v_div_fmas_f32 v34, v34, v42, v47
	v_div_fixup_f32 v19, v34, v19, 1.0
	v_div_scale_f32 v34, s[10:11], v18, v18, 1.0
	v_rcp_f32_e32 v42, v34
	s_nop 0
	v_fma_f32 v43, -v34, v42, 1.0
	v_fmac_f32_e32 v42, v43, v42
	v_div_scale_f32 v43, vcc, 1.0, v18, 1.0
	v_mul_f32_e32 v47, v43, v42
	v_fma_f32 v49, -v34, v47, v43
	v_fmac_f32_e32 v47, v49, v42
	v_fma_f32 v34, -v34, v47, v43
	v_div_fmas_f32 v34, v34, v42, v47
	v_div_fixup_f32 v18, v34, v18, 1.0
	v_lshlrev_b32_e32 v34, 16, v35
	v_and_b32_e32 v35, 0xffff0000, v35
	v_pk_mul_f32 v[18:19], v[18:19], v[34:35]
	v_pk_mul_f32 v[42:43], v[16:17], v[16:17]
	v_cvt_pk_bf16_f32 v16, v16, v17
	v_cvt_pk_bf16_f32 v17, v18, v19
	global_store_dwordx2 v[44:45], v[16:17], off offset:1536
	v_pk_mul_f32 v[34:35], v[18:19], v[18:19]
	global_load_dwordx4 v[16:19], v[38:39], off offset:32
	s_waitcnt vmcnt(0)
	v_add_f32_e32 v16, v20, v16
	v_add_f32_e32 v17, v21, v17
	v_mul_f32_e32 v16, 0xbfb8aa3b, v16
	v_mul_f32_e32 v17, 0xbfb8aa3b, v17
	v_exp_f32_e32 v16, v16
	v_exp_f32_e32 v17, v17
	v_add_f32_e32 v18, v22, v18
	v_mul_f32_e32 v18, 0xbfb8aa3b, v18
	v_exp_f32_e32 v20, v18
	v_add_f32_e32 v18, v23, v19
	v_mul_f32_e32 v18, 0xbfb8aa3b, v18
	v_pk_add_f32 v[16:17], v[16:17], 1.0 op_sel_hi:[1,0]
	v_exp_f32_e32 v21, v18
	v_div_scale_f32 v18, s[10:11], v17, v17, 1.0
	v_rcp_f32_e32 v19, v18
	v_pk_add_f32 v[20:21], v[20:21], 1.0 op_sel_hi:[1,0]
	v_fma_f32 v22, -v18, v19, 1.0
	v_fmac_f32_e32 v19, v22, v19
	v_div_scale_f32 v22, vcc, 1.0, v17, 1.0
	v_mul_f32_e32 v23, v22, v19
	v_fma_f32 v47, -v18, v23, v22
	v_fmac_f32_e32 v23, v47, v19
	v_fma_f32 v18, -v18, v23, v22
	v_div_fmas_f32 v18, v18, v19, v23
	v_div_fixup_f32 v23, v18, v17, 1.0
	v_div_scale_f32 v17, s[10:11], v16, v16, 1.0
	v_rcp_f32_e32 v18, v17
	s_nop 0
	v_fma_f32 v19, -v17, v18, 1.0
	v_fmac_f32_e32 v18, v19, v18
	v_div_scale_f32 v19, vcc, 1.0, v16, 1.0
	v_mul_f32_e32 v22, v19, v18
	v_fma_f32 v47, -v17, v22, v19
	v_fmac_f32_e32 v22, v47, v18
	v_fma_f32 v17, -v17, v22, v19
	v_div_fmas_f32 v17, v17, v18, v22
	v_div_fixup_f32 v22, v17, v16, 1.0
	ds_read2_b64 v[16:19], v46 offset0:4 offset1:6
	v_lshlrev_b32_e32 v46, 16, v36
	v_and_b32_e32 v47, 0xffff0000, v36
	v_pk_mul_f32 v[46:47], v[22:23], v[46:47]
	v_div_scale_f32 v22, s[10:11], v21, v21, 1.0
	v_rcp_f32_e32 v23, v22
	s_nop 0
	v_fma_f32 v36, -v22, v23, 1.0
	v_fmac_f32_e32 v23, v36, v23
	v_div_scale_f32 v36, vcc, 1.0, v21, 1.0
	v_mul_f32_e32 v49, v36, v23
	v_fma_f32 v50, -v22, v49, v36
	v_fmac_f32_e32 v49, v50, v23
	v_fma_f32 v22, -v22, v49, v36
	v_div_fmas_f32 v22, v22, v23, v49
	v_div_fixup_f32 v21, v22, v21, 1.0
	v_div_scale_f32 v22, s[10:11], v20, v20, 1.0
	v_rcp_f32_e32 v23, v22
	s_nop 0
	v_fma_f32 v36, -v22, v23, 1.0
	v_fmac_f32_e32 v23, v36, v23
	v_div_scale_f32 v36, vcc, 1.0, v20, 1.0
	v_mul_f32_e32 v49, v36, v23
	v_fma_f32 v50, -v22, v49, v36
	v_fmac_f32_e32 v49, v50, v23
	v_fma_f32 v22, -v22, v49, v36
	v_div_fmas_f32 v22, v22, v23, v49
	v_div_fixup_f32 v20, v22, v20, 1.0
	v_lshlrev_b32_e32 v22, 16, v37
	v_and_b32_e32 v23, 0xffff0000, v37
	v_pk_mul_f32 v[36:37], v[20:21], v[22:23]
	v_pk_mul_f32 v[22:23], v[46:47], v[46:47]
	v_cvt_pk_bf16_f32 v46, v46, v47
	v_cvt_pk_bf16_f32 v47, v36, v37
	global_store_dwordx2 v[44:45], v[46:47], off offset:1552
	global_load_dwordx4 v[50:53], v[38:39], off offset:64
	v_pk_mul_f32 v[20:21], v[36:37], v[36:37]
	v_add_f32_e32 v22, v22, v23
	v_add_f32_e32 v20, v20, v22
	v_add_f32_e32 v20, v21, v20
	s_waitcnt vmcnt(0)
; DI unsigned pk2(float a, float b) { f2_t v = {a, b}; bf2_t r = __builtin_convertvector(v, bf2_t); return __builtin_bit_cast(unsigned, r); }
; DI float bflo(unsigned u) { return __uint_as_float(u << 16); }
; DI float bfhi(unsigned u) { return __uint_as_float(u & 0xffff0000u); }
; DI float shx32(float v) { return shx(v, get_tid() & 63, 32); }
; DI void ssm_out_item(const CP& p, int l, int item, char* smem) {
;     ...
; #pragma unroll
;     for (int blk = 0; blk < 4; ++blk) {
;       const int ch = w * 32 + 8 * blk + 4 * hh;
;       const fl4 bv = *(const fl4*)(bg + ch);
;       const u32x2 yy = *(const u32x2*)(sY + token * 264 + ch);
;       const float g0 = 1.f / (1.f + __expf(-(acc[j][4 * blk] + bv.x)));
;       const float g1 = 1.f / (1.f + __expf(-(acc[j][4 * blk + 1] + bv.y)));
;       const float g2 = 1.f / (1.f + __expf(-(acc[j][4 * blk + 2] + bv.z)));
;       const float g3 = 1.f / (1.f + __expf(-(acc[j][4 * blk + 3] + bv.w)));
;       const float o0 = bflo(yy.x) * g0, o1 = bfhi(yy.x) * g1, o2 = bflo(yy.y) * g2, o3 = bfhi(yy.y) * g3;
;       sq += o0 * o0 + o1 * o1 + o2 * o2 + o3 * o3;
;       u32x2 v;
;       v.x = pk2(o0, o1); v.y = pk2(o2, o3);
;       *(u32x2*)(p.mixed + (tok0 + token) * 1024 + 768 + ch) = v;
;     }
;     sq += shx32(sq);
;     if (hh == 0) sSS[w * 64 + token] = sq;
	v_add_f32_e32 v24, v24, v50
	v_add_f32_e32 v25, v25, v51
	v_mul_f32_e32 v24, 0xbfb8aa3b, v24
	v_mul_f32_e32 v25, 0xbfb8aa3b, v25
	v_exp_f32_e32 v24, v24
	v_exp_f32_e32 v25, v25
	v_add_f32_e32 v26, v26, v52
	v_add_f32_e32 v27, v27, v53
	v_mul_f32_e32 v26, 0xbfb8aa3b, v26
	v_pk_add_f32 v[24:25], v[24:25], 1.0 op_sel_hi:[1,0]
	v_mul_f32_e32 v27, 0xbfb8aa3b, v27
	v_div_scale_f32 v36, s[10:11], v25, v25, 1.0
	v_rcp_f32_e32 v37, v36
	v_exp_f32_e32 v26, v26
	v_exp_f32_e32 v27, v27
	v_fma_f32 v46, -v36, v37, 1.0
	v_fmac_f32_e32 v37, v46, v37
	v_div_scale_f32 v46, vcc, 1.0, v25, 1.0
	v_mul_f32_e32 v47, v46, v37
	v_fma_f32 v49, -v36, v47, v46
	v_fmac_f32_e32 v47, v49, v37
	v_fma_f32 v36, -v36, v47, v46
	v_div_fmas_f32 v36, v36, v37, v47
	v_div_fixup_f32 v25, v36, v25, 1.0
	v_div_scale_f32 v36, s[10:11], v24, v24, 1.0
	v_rcp_f32_e32 v37, v36
	v_pk_add_f32 v[26:27], v[26:27], 1.0 op_sel_hi:[1,0]
	v_fma_f32 v46, -v36, v37, 1.0
	v_fmac_f32_e32 v37, v46, v37
	v_div_scale_f32 v46, vcc, 1.0, v24, 1.0
	v_mul_f32_e32 v47, v46, v37
	v_fma_f32 v49, -v36, v47, v46
	v_fmac_f32_e32 v47, v49, v37
	v_fma_f32 v36, -v36, v47, v46
	v_div_fmas_f32 v36, v36, v37, v47
	v_div_fixup_f32 v24, v36, v24, 1.0
	s_waitcnt lgkmcnt(0)
	v_lshlrev_b32_e32 v36, 16, v16
	v_and_b32_e32 v37, 0xffff0000, v16
	v_div_scale_f32 v16, s[10:11], v27, v27, 1.0
	v_pk_mul_f32 v[24:25], v[24:25], v[36:37]
	v_rcp_f32_e32 v36, v16
	s_nop 0
	v_fma_f32 v37, -v16, v36, 1.0
	v_fmac_f32_e32 v36, v37, v36
	v_div_scale_f32 v37, vcc, 1.0, v27, 1.0
	v_mul_f32_e32 v46, v37, v36
	v_fma_f32 v47, -v16, v46, v37
	v_fmac_f32_e32 v46, v47, v36
	v_fma_f32 v16, -v16, v46, v37
	v_div_fmas_f32 v16, v16, v36, v46
	v_div_fixup_f32 v27, v16, v27, 1.0
	v_div_scale_f32 v16, s[10:11], v26, v26, 1.0
	v_rcp_f32_e32 v36, v16
	s_nop 0
	v_fma_f32 v37, -v16, v36, 1.0
	v_fmac_f32_e32 v36, v37, v36
	v_div_scale_f32 v37, vcc, 1.0, v26, 1.0
	v_mul_f32_e32 v46, v37, v36
	v_fma_f32 v47, -v16, v46, v37
	v_fmac_f32_e32 v46, v47, v36
	v_fma_f32 v16, -v16, v46, v37
	v_div_fmas_f32 v16, v16, v36, v46
	v_div_fixup_f32 v26, v16, v26, 1.0
	v_lshlrev_b32_e32 v16, 16, v17
	v_and_b32_e32 v17, 0xffff0000, v17
	v_pk_mul_f32 v[36:37], v[26:27], v[16:17]
	v_pk_mul_f32 v[26:27], v[24:25], v[24:25]
	v_cvt_pk_bf16_f32 v24, v24, v25
	v_cvt_pk_bf16_f32 v25, v36, v37
	global_store_dwordx2 v[44:45], v[24:25], off offset:1568
	global_load_dwordx4 v[50:53], v[38:39], off offset:96
	v_pk_mul_f32 v[16:17], v[36:37], v[36:37]
	v_add_f32_e32 v21, v26, v27
	v_add_f32_e32 v16, v16, v21
	v_add_f32_e32 v16, v17, v16
	v_lshl_add_u32 v26, v56, 2, v48
	s_waitcnt vmcnt(0)
	v_add_f32_e32 v24, v28, v50
	v_add_f32_e32 v25, v29, v51
	v_mul_f32_e32 v24, 0xbfb8aa3b, v24
	v_mul_f32_e32 v25, 0xbfb8aa3b, v25
	v_exp_f32_e32 v24, v24
	v_exp_f32_e32 v25, v25
	v_add_f32_e32 v28, v30, v52
	v_add_f32_e32 v29, v31, v53
	v_mul_f32_e32 v28, 0xbfb8aa3b, v28
	v_pk_add_f32 v[24:25], v[24:25], 1.0 op_sel_hi:[1,0]
	v_mul_f32_e32 v29, 0xbfb8aa3b, v29
	v_div_scale_f32 v30, s[10:11], v25, v25, 1.0
	v_rcp_f32_e32 v31, v30
	v_exp_f32_e32 v28, v28
	v_exp_f32_e32 v29, v29
	v_fma_f32 v36, -v30, v31, 1.0
	v_fmac_f32_e32 v31, v36, v31
	v_div_scale_f32 v36, vcc, 1.0, v25, 1.0
	v_mul_f32_e32 v37, v36, v31
	v_fma_f32 v46, -v30, v37, v36
	v_fmac_f32_e32 v37, v46, v31
	v_fma_f32 v30, -v30, v37, v36
	v_div_fmas_f32 v30, v30, v31, v37
	v_div_fixup_f32 v25, v30, v25, 1.0
	v_div_scale_f32 v30, s[10:11], v24, v24, 1.0
	v_rcp_f32_e32 v31, v30
	v_pk_add_f32 v[28:29], v[28:29], 1.0 op_sel_hi:[1,0]
	v_fma_f32 v36, -v30, v31, 1.0
	v_fmac_f32_e32 v31, v36, v31
	v_div_scale_f32 v36, vcc, 1.0, v24, 1.0
	v_mul_f32_e32 v37, v36, v31
	v_fma_f32 v46, -v30, v37, v36
	v_fmac_f32_e32 v37, v46, v31
	v_fma_f32 v30, -v30, v37, v36
	v_div_fmas_f32 v30, v30, v31, v37
	v_div_fixup_f32 v24, v30, v24, 1.0
	v_lshlrev_b32_e32 v30, 16, v18
	v_and_b32_e32 v31, 0xffff0000, v18
	v_div_scale_f32 v18, s[10:11], v29, v29, 1.0
	v_pk_mul_f32 v[24:25], v[24:25], v[30:31]
	v_rcp_f32_e32 v30, v18
	s_nop 0
	v_fma_f32 v31, -v18, v30, 1.0
	v_fmac_f32_e32 v30, v31, v30
	v_div_scale_f32 v31, vcc, 1.0, v29, 1.0
	v_mul_f32_e32 v36, v31, v30
	v_fma_f32 v37, -v18, v36, v31
	v_fmac_f32_e32 v36, v37, v30
	v_fma_f32 v18, -v18, v36, v31
	v_div_fmas_f32 v18, v18, v30, v36
	v_div_fixup_f32 v29, v18, v29, 1.0
	v_div_scale_f32 v18, s[10:11], v28, v28, 1.0
	v_rcp_f32_e32 v30, v18
	s_nop 0
	v_fma_f32 v31, -v18, v30, 1.0
	v_fmac_f32_e32 v30, v31, v30
	v_div_scale_f32 v31, vcc, 1.0, v28, 1.0
	v_mul_f32_e32 v36, v31, v30
	v_fma_f32 v37, -v18, v36, v31
	v_fmac_f32_e32 v36, v37, v30
	v_fma_f32 v18, -v18, v36, v31
	v_div_fmas_f32 v18, v18, v30, v36
	v_div_fixup_f32 v28, v18, v28, 1.0
	v_lshlrev_b32_e32 v18, 16, v19
	v_and_b32_e32 v19, 0xffff0000, v19
	v_add_f32_e32 v36, v42, v43
	v_pk_mul_f32 v[18:19], v[28:29], v[18:19]
	v_pk_mul_f32 v[28:29], v[24:25], v[24:25]
	v_add_f32_e32 v34, v34, v36
	v_pk_mul_f32 v[30:31], v[18:19], v[18:19]
	v_add_f32_e32 v34, v35, v34
	v_add_f32_e32 v17, v28, v29
	v_add_f32_e32 v20, v34, v20
	v_add_f32_e32 v17, v30, v17
	v_add_f32_e32 v16, v20, v16
	v_add_f32_e32 v17, v31, v17
	v_add_f32_e32 v16, v16, v17
	v_cvt_pk_bf16_f32 v20, v24, v25
	v_cvt_pk_bf16_f32 v21, v18, v19
	v_mov_b32_e32 v17, v202
	global_store_dwordx2 v[44:45], v[20:21], off offset:1584
	s_nop 0
	v_lshlrev_b32_e32 v17, 2, v17
	v_bitop3_b32 v17, v17, s84, v211 bitop3:0x6c
	ds_bpermute_b32 v17, v17, v16
	s_and_saveexec_b64 s[10:11], s[4:5]
	s_cbranch_execz .LBB0_339
	s_waitcnt lgkmcnt(0)
	v_add_f32_e32 v16, v16, v17
	ds_write_b32 v26, v16

; DI int get_tid() { int t = __builtin_amdgcn_workitem_id_x(); asm volatile("" : "+v"(t)); return t; }
; DI void ssm_carry_item(const CP& p, int l, int item, char* smem) {
;   const int tid = get_tid();
;   const int gl = tid & 31, sc = tid >> 5;
;   const int q = item * 32 + gl, b = q >> 10, gp = q & 1023;
;   fl2* sE = (fl2*)smem;
;   const fl4 ac = *(const fl4*)(p.ssmc + ((size_t)l * 1024 + gp) * 4);
;   const float ar = ac.z, ai = ac.w;
;   fl2 xe[16];
; #pragma unroll
;   for (int j = 0; j < 16; ++j) xe[j] = *(const fl2*)(p.xend + (((size_t)b * NCH + sc * 16 + j) * 1024 + gp) * 2);
;   float sr = 0.f, si = 0.f;
; #pragma unroll
;   for (int j = 0; j < 16; ++j) {
;     const float lr = sr, li = si;
;     const float nr = ar * sr - ai * si + xe[j].x;
;     const float ni = ar * si + ai * sr + xe[j].y;
;     sr = nr; si = ni;
;     xe[j].x = lr; xe[j].y = li;
;   }
;   fl2 e = {sr, si};
;   sE[sc * 32 + gl] = e;
;   float pr = ar, pi = ai;
; #pragma unroll
;   for (int i = 0; i < 4; ++i) { const float t = pr * pr - pi * pi; pi = 2.f * pr * pi; pr = t; }
;   __syncthreads();
;   float cr = 0.f, ci = 0.f;
;   for (int s2 = 0; s2 < sc; ++s2) {
;     const fl2 v = sE[s2 * 32 + gl];
;     const float nr = pr * cr - pi * ci + v.x;
;     const float ni = pr * ci + pi * cr + v.y;
;     cr = nr; ci = ni;
;   }
;   float wr = 1.f, wi = 0.f;
; #pragma unroll
;   for (int j = 0; j < 16; ++j) {
;     fl2 o = {xe[j].x + wr * cr - wi * ci, xe[j].y + wr * ci + wi * cr};
;     *(fl2*)(p.cin + (((size_t)b * NCH + sc * 16 + j) * 1024 + gp) * 2) = o;
;     const float t = wr * ar - wi * ai; wi = wr * ai + wi * ar; wr = t;
;   }
;   __syncthreads();
.LBB0_381:
	s_and_b64 vcc, exec, s[4:5]
	s_cbranch_vccz .LBB0_389
	v_readlane_b32 s4, v255, 8
	v_readlane_b32 s5, v255, 9
	s_andn2_b64 vcc, exec, s[4:5]
	s_cbranch_vccnz .LBB0_389
	s_load_dwordx2 s[10:11], s[0:1], 0x130
	s_load_dwordx4 s[4:7], s[0:1], 0x120
	s_load_dwordx2 s[100:101], s[0:1], 0x170
	s_mov_b32 s65, s49
	s_lshl_b64 s[12:13], s[64:65], 14
	s_mov_b32 s16, s2
	v_mov_b32_e32 v90, 1
	s_waitcnt lgkmcnt(0)
	s_lshl_b32 s8, s64, 2
	s_addk_i32 s8, 0xa0
	s_add_u32 s100, s100, s8
	s_addc_u32 s101, s101, 0
	s_add_u32 s10, s10, s12
	s_addc_u32 s11, s11, s13
	s_branch .LBB0_385
.LBB0_384:
	s_or_b64 exec, exec, s[12:13]
	v_pk_add_f32 v[72:73], v[38:39], 0 op_sel_hi:[1,0]
	v_pk_mul_f32 v[74:75], v[38:39], 0 op_sel_hi:[1,0]
	v_lshl_add_u64 v[70:71], s[6:7], 0, v[32:33]
	v_pk_add_f32 v[76:77], v[72:73], v[74:75] op_sel:[0,1] op_sel_hi:[1,0] neg_lo:[0,1] neg_hi:[0,1]
	v_pk_add_f32 v[72:73], v[72:73], v[74:75] op_sel:[0,1] op_sel_hi:[1,0]
	v_lshl_add_u64 v[50:51], v[70:71], 0, v[50:51]
	v_mov_b32_e32 v77, v73
	global_store_dwordx2 v[50:51], v[76:77], off sc1
	v_pk_add_f32 v[50:51], v[2:3], v[66:67] op_sel:[1,0] op_sel_hi:[0,1] neg_lo:[0,1] neg_hi:[0,1]
	v_pk_add_f32 v[66:67], v[2:3], v[66:67] op_sel:[1,0] op_sel_hi:[0,1]
	v_mov_b32_e32 v73, v51
	v_pk_mov_b32 v[74:75], v[50:51], v[66:67] op_sel:[1,0]
	v_pk_fma_f32 v[50:51], v[50:51], v[38:39], v[68:69] op_sel:[1,0,0]
	v_mov_b32_e32 v72, v66
	v_pk_fma_f32 v[68:69], v[66:67], v[38:39], v[50:51] op_sel:[0,1,0] op_sel_hi:[1,0,1] neg_lo:[1,0,0] neg_hi:[1,0,0]
	v_pk_fma_f32 v[50:51], v[66:67], v[38:39], v[50:51] op_sel:[0,1,0] op_sel_hi:[0,0,1]
	v_mov_b32_e32 v69, v51
	v_lshl_add_u64 v[44:45], v[70:71], 0, v[44:45]
	global_store_dwordx2 v[44:45], v[68:69], off sc1
	v_pk_mul_f32 v[44:45], v[2:3], v[74:75]
	v_pk_mul_f32 v[50:51], v[2:3], v[72:73]
	v_lshl_add_u64 v[46:47], v[70:71], 0, v[46:47]
	v_pk_mov_b32 v[66:67], v[50:51], v[44:45] op_sel:[1,0]
	v_mov_b32_e32 v51, v45
	v_pk_add_f32 v[44:45], v[66:67], v[50:51] neg_lo:[0,1] neg_hi:[0,1]
	v_pk_add_f32 v[50:51], v[66:67], v[50:51]
	v_mov_b32_e32 v67, v45
	v_pk_mov_b32 v[68:69], v[44:45], v[50:51] op_sel:[1,0]
	v_pk_fma_f32 v[44:45], v[44:45], v[38:39], v[64:65] op_sel:[1,0,0]
	v_mov_b32_e32 v66, v50
	v_pk_fma_f32 v[64:65], v[50:51], v[38:39], v[44:45] op_sel:[0,1,0] op_sel_hi:[1,0,1] neg_lo:[1,0,0] neg_hi:[1,0,0]
	v_pk_fma_f32 v[44:45], v[50:51], v[38:39], v[44:45] op_sel:[0,1,0] op_sel_hi:[0,0,1]
	v_mov_b32_e32 v65, v45
	global_store_dwordx2 v[46:47], v[64:65], off sc1
	v_pk_mul_f32 v[44:45], v[2:3], v[68:69]
	v_pk_mul_f32 v[46:47], v[2:3], v[66:67]
	v_lshl_add_u64 v[40:41], v[70:71], 0, v[40:41]
	v_pk_mov_b32 v[50:51], v[46:47], v[44:45] op_sel:[1,0]
	v_mov_b32_e32 v47, v45
	v_pk_add_f32 v[44:45], v[50:51], v[46:47] neg_lo:[0,1] neg_hi:[0,1]
	v_pk_add_f32 v[46:47], v[50:51], v[46:47]
	v_mov_b32_e32 v51, v45
	v_pk_mov_b32 v[64:65], v[44:45], v[46:47] op_sel:[1,0]
	v_pk_fma_f32 v[44:45], v[44:45], v[38:39], v[62:63] op_sel:[1,0,0]
	v_mov_b32_e32 v50, v46
	v_pk_fma_f32 v[62:63], v[46:47], v[38:39], v[44:45] op_sel:[0,1,0] op_sel_hi:[1,0,1] neg_lo:[1,0,0] neg_hi:[1,0,0]
	v_pk_fma_f32 v[44:45], v[46:47], v[38:39], v[44:45] op_sel:[0,1,0] op_sel_hi:[0,0,1]
	v_mov_b32_e32 v63, v45
	global_store_dwordx2 v[40:41], v[62:63], off sc1
	v_pk_mul_f32 v[40:41], v[2:3], v[64:65]
	v_pk_mul_f32 v[44:45], v[2:3], v[50:51]
	v_lshl_add_u64 v[34:35], v[70:71], 0, v[34:35]
	v_pk_mov_b32 v[46:47], v[44:45], v[40:41] op_sel:[1,0]
	v_mov_b32_e32 v45, v41
	v_pk_add_f32 v[40:41], v[46:47], v[44:45] neg_lo:[0,1] neg_hi:[0,1]
	v_pk_add_f32 v[44:45], v[46:47], v[44:45]
	v_mov_b32_e32 v47, v41
	v_pk_mov_b32 v[50:51], v[40:41], v[44:45] op_sel:[1,0]
	v_pk_fma_f32 v[40:41], v[40:41], v[38:39], v[60:61] op_sel:[1,0,0]
	v_mov_b32_e32 v46, v44
	v_pk_fma_f32 v[60:61], v[44:45], v[38:39], v[40:41] op_sel:[0,1,0] op_sel_hi:[1,0,1] neg_lo:[1,0,0] neg_hi:[1,0,0]
	v_pk_fma_f32 v[40:41], v[44:45], v[38:39], v[40:41] op_sel:[0,1,0] op_sel_hi:[0,0,1]
	v_mov_b32_e32 v61, v41
	global_store_dwordx2 v[34:35], v[60:61], off sc1
	v_pk_mul_f32 v[34:35], v[2:3], v[50:51]
	v_pk_mul_f32 v[40:41], v[2:3], v[46:47]
	v_lshl_add_u64 v[28:29], v[70:71], 0, v[28:29]
	v_pk_mov_b32 v[44:45], v[40:41], v[34:35] op_sel:[1,0]
	v_mov_b32_e32 v41, v35
	v_pk_add_f32 v[34:35], v[44:45], v[40:41] neg_lo:[0,1] neg_hi:[0,1]
	v_pk_add_f32 v[40:41], v[44:45], v[40:41]
	v_mov_b32_e32 v45, v35
	v_pk_mov_b32 v[46:47], v[34:35], v[40:41] op_sel:[1,0]
	v_pk_fma_f32 v[34:35], v[34:35], v[38:39], v[58:59] op_sel:[1,0,0]
	v_mov_b32_e32 v44, v40
	v_pk_fma_f32 v[50:51], v[40:41], v[38:39], v[34:35] op_sel:[0,1,0] op_sel_hi:[1,0,1] neg_lo:[1,0,0] neg_hi:[1,0,0]
	v_pk_fma_f32 v[34:35], v[40:41], v[38:39], v[34:35] op_sel:[0,1,0] op_sel_hi:[0,0,1]
	v_mov_b32_e32 v51, v35
	global_store_dwordx2 v[28:29], v[50:51], off sc1
	v_pk_mul_f32 v[28:29], v[2:3], v[46:47]
	v_pk_mul_f32 v[34:35], v[2:3], v[44:45]
	v_lshl_add_u64 v[24:25], v[70:71], 0, v[24:25]
	v_pk_mov_b32 v[40:41], v[34:35], v[28:29] op_sel:[1,0]
	v_mov_b32_e32 v35, v29
	v_pk_add_f32 v[28:29], v[40:41], v[34:35] neg_lo:[0,1] neg_hi:[0,1]
	v_pk_add_f32 v[34:35], v[40:41], v[34:35]
	v_mov_b32_e32 v41, v29
	v_pk_mov_b32 v[44:45], v[28:29], v[34:35] op_sel:[1,0]
	v_pk_fma_f32 v[28:29], v[28:29], v[38:39], v[56:57] op_sel:[1,0,0]
	v_mov_b32_e32 v40, v34
	v_pk_fma_f32 v[46:47], v[34:35], v[38:39], v[28:29] op_sel:[0,1,0] op_sel_hi:[1,0,1] neg_lo:[1,0,0] neg_hi:[1,0,0]
	v_pk_fma_f32 v[28:29], v[34:35], v[38:39], v[28:29] op_sel:[0,1,0] op_sel_hi:[0,0,1]
	v_mov_b32_e32 v47, v29
	global_store_dwordx2 v[24:25], v[46:47], off sc1
	v_pk_mul_f32 v[24:25], v[2:3], v[44:45]
; DI void ssm_carry_item(const CP& p, int l, int item, char* smem) {
;     ...
;   float wr = 1.f, wi = 0.f;
; #pragma unroll
;   for (int j = 0; j < 16; ++j) {
;     fl2 o = {xe[j].x + wr * cr - wi * ci, xe[j].y + wr * ci + wi * cr};
;     *(fl2*)(p.cin + (((size_t)b * NCH + sc * 16 + j) * 1024 + gp) * 2) = o;
;     const float t = wr * ar - wi * ai; wi = wr * ai + wi * ar; wr = t;
;   }
;   __syncthreads();
; template <bool DRY>
; DI void run_phase(const CP& p, int ph, int l, char* smem) {
;     ...
;       for (int it = b0; it < 64; it += nb) ssm_carry_item(p, l, it, smem);
	v_pk_mul_f32 v[28:29], v[2:3], v[40:41]
	v_lshl_add_u64 v[18:19], v[70:71], 0, v[18:19]
	v_pk_mov_b32 v[34:35], v[28:29], v[24:25] op_sel:[1,0]
	v_mov_b32_e32 v29, v25
	v_pk_add_f32 v[24:25], v[34:35], v[28:29] neg_lo:[0,1] neg_hi:[0,1]
	v_pk_add_f32 v[28:29], v[34:35], v[28:29]
	v_mov_b32_e32 v35, v25
	v_pk_mov_b32 v[40:41], v[24:25], v[28:29] op_sel:[1,0]
	v_pk_fma_f32 v[24:25], v[24:25], v[38:39], v[54:55] op_sel:[1,0,0]
	v_mov_b32_e32 v34, v28
	v_pk_fma_f32 v[44:45], v[28:29], v[38:39], v[24:25] op_sel:[0,1,0] op_sel_hi:[1,0,1] neg_lo:[1,0,0] neg_hi:[1,0,0]
	v_pk_fma_f32 v[24:25], v[28:29], v[38:39], v[24:25] op_sel:[0,1,0] op_sel_hi:[0,0,1]
	v_mov_b32_e32 v45, v25
	global_store_dwordx2 v[18:19], v[44:45], off sc1
	v_pk_mul_f32 v[18:19], v[2:3], v[40:41]
	v_pk_mul_f32 v[24:25], v[2:3], v[34:35]
	v_lshl_add_u64 v[16:17], v[70:71], 0, v[16:17]
	v_pk_mov_b32 v[28:29], v[24:25], v[18:19] op_sel:[1,0]
	v_mov_b32_e32 v25, v19
	v_pk_add_f32 v[18:19], v[28:29], v[24:25] neg_lo:[0,1] neg_hi:[0,1]
	v_pk_add_f32 v[24:25], v[28:29], v[24:25]
	v_mov_b32_e32 v29, v19
	v_pk_mov_b32 v[34:35], v[18:19], v[24:25] op_sel:[1,0]
	v_pk_fma_f32 v[18:19], v[18:19], v[38:39], v[52:53] op_sel:[1,0,0]
	v_mov_b32_e32 v28, v24
	v_pk_fma_f32 v[40:41], v[24:25], v[38:39], v[18:19] op_sel:[0,1,0] op_sel_hi:[1,0,1] neg_lo:[1,0,0] neg_hi:[1,0,0]
	v_pk_fma_f32 v[18:19], v[24:25], v[38:39], v[18:19] op_sel:[0,1,0] op_sel_hi:[0,0,1]
	v_mov_b32_e32 v41, v19
	global_store_dwordx2 v[16:17], v[40:41], off sc1
	v_pk_mul_f32 v[16:17], v[2:3], v[34:35]
	v_pk_mul_f32 v[18:19], v[2:3], v[28:29]
	v_lshl_add_u64 v[14:15], v[70:71], 0, v[14:15]
	v_pk_mov_b32 v[24:25], v[18:19], v[16:17] op_sel:[1,0]
	v_mov_b32_e32 v19, v17
	v_pk_add_f32 v[16:17], v[24:25], v[18:19] neg_lo:[0,1] neg_hi:[0,1]
	v_pk_add_f32 v[18:19], v[24:25], v[18:19]
	v_mov_b32_e32 v25, v17
	v_pk_mov_b32 v[28:29], v[16:17], v[18:19] op_sel:[1,0]
	v_pk_fma_f32 v[16:17], v[16:17], v[38:39], v[48:49] op_sel:[1,0,0]
	v_mov_b32_e32 v24, v18
	v_pk_fma_f32 v[34:35], v[18:19], v[38:39], v[16:17] op_sel:[0,1,0] op_sel_hi:[1,0,1] neg_lo:[1,0,0] neg_hi:[1,0,0]
	v_pk_fma_f32 v[16:17], v[18:19], v[38:39], v[16:17] op_sel:[0,1,0] op_sel_hi:[0,0,1]
	v_mov_b32_e32 v35, v17
	global_store_dwordx2 v[14:15], v[34:35], off sc1
	v_pk_mul_f32 v[14:15], v[2:3], v[28:29]
	v_pk_mul_f32 v[16:17], v[2:3], v[24:25]
	v_lshl_add_u64 v[12:13], v[70:71], 0, v[12:13]
	v_pk_mov_b32 v[18:19], v[16:17], v[14:15] op_sel:[1,0]
	v_mov_b32_e32 v17, v15
	v_pk_add_f32 v[14:15], v[18:19], v[16:17] neg_lo:[0,1] neg_hi:[0,1]
	v_pk_add_f32 v[16:17], v[18:19], v[16:17]
	v_mov_b32_e32 v19, v15
	v_pk_mov_b32 v[24:25], v[14:15], v[16:17] op_sel:[1,0]
	v_pk_fma_f32 v[14:15], v[14:15], v[38:39], v[42:43] op_sel:[1,0,0]
	v_mov_b32_e32 v18, v16
	v_pk_fma_f32 v[28:29], v[16:17], v[38:39], v[14:15] op_sel:[0,1,0] op_sel_hi:[1,0,1] neg_lo:[1,0,0] neg_hi:[1,0,0]
	v_pk_fma_f32 v[14:15], v[16:17], v[38:39], v[14:15] op_sel:[0,1,0] op_sel_hi:[0,0,1]
	v_mov_b32_e32 v29, v15
	global_store_dwordx2 v[12:13], v[28:29], off sc1
	v_pk_mul_f32 v[12:13], v[2:3], v[24:25]
	v_pk_mul_f32 v[14:15], v[2:3], v[18:19]
	v_lshl_add_u64 v[10:11], v[70:71], 0, v[10:11]
	v_pk_mov_b32 v[16:17], v[14:15], v[12:13] op_sel:[1,0]
	v_mov_b32_e32 v15, v13
	v_pk_add_f32 v[12:13], v[16:17], v[14:15] neg_lo:[0,1] neg_hi:[0,1]
	v_pk_add_f32 v[14:15], v[16:17], v[14:15]
	v_mov_b32_e32 v17, v13
	v_pk_mov_b32 v[18:19], v[12:13], v[14:15] op_sel:[1,0]
	v_pk_fma_f32 v[12:13], v[12:13], v[38:39], v[36:37] op_sel:[1,0,0]
	v_mov_b32_e32 v16, v14
	v_pk_fma_f32 v[24:25], v[14:15], v[38:39], v[12:13] op_sel:[0,1,0] op_sel_hi:[1,0,1] neg_lo:[1,0,0] neg_hi:[1,0,0]
	v_pk_fma_f32 v[12:13], v[14:15], v[38:39], v[12:13] op_sel:[0,1,0] op_sel_hi:[0,0,1]
	v_mov_b32_e32 v25, v13
	global_store_dwordx2 v[10:11], v[24:25], off sc1
	v_pk_mul_f32 v[10:11], v[2:3], v[18:19]
	v_pk_mul_f32 v[12:13], v[2:3], v[16:17]
	v_lshl_add_u64 v[8:9], v[70:71], 0, v[8:9]
	v_pk_mov_b32 v[14:15], v[12:13], v[10:11] op_sel:[1,0]
	v_mov_b32_e32 v13, v11
	v_pk_add_f32 v[10:11], v[14:15], v[12:13] neg_lo:[0,1] neg_hi:[0,1]
	v_pk_add_f32 v[12:13], v[14:15], v[12:13]
	v_mov_b32_e32 v15, v11
	v_pk_mov_b32 v[16:17], v[10:11], v[12:13] op_sel:[1,0]
	v_pk_fma_f32 v[10:11], v[10:11], v[38:39], v[30:31] op_sel:[1,0,0]
	v_mov_b32_e32 v14, v12
	v_pk_fma_f32 v[18:19], v[12:13], v[38:39], v[10:11] op_sel:[0,1,0] op_sel_hi:[1,0,1] neg_lo:[1,0,0] neg_hi:[1,0,0]
	v_pk_fma_f32 v[10:11], v[12:13], v[38:39], v[10:11] op_sel:[0,1,0] op_sel_hi:[0,0,1]
	v_mov_b32_e32 v19, v11
	global_store_dwordx2 v[8:9], v[18:19], off sc1
	v_pk_mul_f32 v[8:9], v[2:3], v[16:17]
	v_pk_mul_f32 v[10:11], v[2:3], v[14:15]
	v_lshl_add_u64 v[6:7], v[70:71], 0, v[6:7]
	v_pk_mov_b32 v[12:13], v[10:11], v[8:9] op_sel:[1,0]
	v_mov_b32_e32 v11, v9
	v_pk_add_f32 v[8:9], v[12:13], v[10:11] neg_lo:[0,1] neg_hi:[0,1]
	v_pk_add_f32 v[10:11], v[12:13], v[10:11]
	v_mov_b32_e32 v13, v9
	v_pk_mov_b32 v[14:15], v[8:9], v[10:11] op_sel:[1,0]
	v_pk_fma_f32 v[8:9], v[8:9], v[38:39], v[26:27] op_sel:[1,0,0]
	v_mov_b32_e32 v12, v10
	v_pk_fma_f32 v[16:17], v[10:11], v[38:39], v[8:9] op_sel:[0,1,0] op_sel_hi:[1,0,1] neg_lo:[1,0,0] neg_hi:[1,0,0]
	v_pk_fma_f32 v[8:9], v[10:11], v[38:39], v[8:9] op_sel:[0,1,0] op_sel_hi:[0,0,1]
	v_mov_b32_e32 v17, v9
	global_store_dwordx2 v[6:7], v[16:17], off sc1
	v_pk_mul_f32 v[6:7], v[2:3], v[14:15]
	v_pk_mul_f32 v[8:9], v[2:3], v[12:13]
	v_lshl_add_u64 v[4:5], v[70:71], 0, v[4:5]
	v_pk_mov_b32 v[10:11], v[8:9], v[6:7] op_sel:[1,0]
	v_mov_b32_e32 v9, v7
	v_pk_add_f32 v[6:7], v[10:11], v[8:9] neg_lo:[0,1] neg_hi:[0,1]
	v_pk_add_f32 v[8:9], v[10:11], v[8:9]
	v_mov_b32_e32 v11, v7
	v_pk_mov_b32 v[12:13], v[6:7], v[8:9] op_sel:[1,0]
	v_pk_fma_f32 v[6:7], v[6:7], v[38:39], v[22:23] op_sel:[1,0,0]
	v_mov_b32_e32 v10, v8
	v_pk_fma_f32 v[14:15], v[8:9], v[38:39], v[6:7] op_sel:[0,1,0] op_sel_hi:[1,0,1] neg_lo:[1,0,0] neg_hi:[1,0,0]
	v_pk_fma_f32 v[6:7], v[8:9], v[38:39], v[6:7] op_sel:[0,1,0] op_sel_hi:[0,0,1]
	v_mov_b32_e32 v15, v7
	global_store_dwordx2 v[4:5], v[14:15], off sc1
	v_pk_mul_f32 v[4:5], v[2:3], v[12:13]
	v_pk_mul_f32 v[2:3], v[2:3], v[10:11]
	v_pk_add_f32 v[4:5], v[4:5], v[4:5] op_sel:[0,1] op_sel_hi:[0,1] neg_lo:[0,1] neg_hi:[0,1]
	v_pk_fma_f32 v[4:5], v[4:5], v[38:39], v[20:21]
	v_pk_add_f32 v[2:3], v[2:3], v[2:3] op_sel:[1,0] op_sel_hi:[1,0]
	s_add_i32 s16, s16, s34
	v_pk_fma_f32 v[6:7], v[2:3], v[38:39], v[4:5] op_sel:[0,1,0] op_sel_hi:[1,0,1] neg_lo:[1,0,0] neg_hi:[1,0,0]
	v_pk_fma_f32 v[2:3], v[2:3], v[38:39], v[4:5] op_sel:[0,1,0] op_sel_hi:[1,0,1]
	v_lshl_add_u64 v[0:1], v[70:71], 0, v[0:1]
	v_mov_b32_e32 v7, v3
	s_cmp_gt_i32 s16, 63
	global_store_dwordx2 v[0:1], v[6:7], off sc1
	s_waitcnt vmcnt(0)
	s_mov_b64 s[12:13], exec
	s_mov_b64 exec, 1
	global_atomic_add v33, v90, s[100:101]
	s_mov_b64 exec, s[12:13]
	s_barrier
	s_cbranch_scc1 .LBB0_389

; template <bool DRY>
; DI void run_phase(const CP& p, int ph, int l, char* smem) {
;     ...
;       for (int it = b0; it < 64; it += nb) ssm_carry_item(p, l, it, smem);
;       break;
;     case PH_M3:
;       FOR_QUEUE(it, 1024, p.wq + l * 2 + 1 + (DRY ? 32 : 0)) {
.LBB0_389:
	s_cmp_eq_u32 s99, 2
	s_cbranch_scc1 .Lm3_entry
	s_mov_b64 s[4:5], 0

; __global__ void __launch_bounds__(512, 2) k_mega(P p) {
;   extern __shared__ __attribute__((aligned(16))) char smem[];
	.amdhsa_kernel _Z6k_mega1P
		.amdhsa_group_segment_fixed_size 8448
		.amdhsa_private_segment_fixed_size 0
		.amdhsa_kernarg_size 792
		.amdhsa_user_sgpr_count 2
		.amdhsa_user_sgpr_dispatch_ptr 0
		.amdhsa_user_sgpr_queue_ptr 0
		.amdhsa_user_sgpr_kernarg_segment_ptr 1
		.amdhsa_user_sgpr_dispatch_id 0
		.amdhsa_user_sgpr_kernarg_preload_length 0
		.amdhsa_user_sgpr_kernarg_preload_offset 0
		.amdhsa_user_sgpr_private_segment_size 0
		.amdhsa_uses_dynamic_stack 0
		.amdhsa_enable_private_segment 0
		.amdhsa_system_sgpr_workgroup_id_x 1
		.amdhsa_system_sgpr_workgroup_id_y 0
		.amdhsa_system_sgpr_workgroup_id_z 0
		.amdhsa_system_sgpr_workgroup_info 0
		.amdhsa_system_vgpr_workitem_id 2
		.amdhsa_next_free_vgpr 256
		.amdhsa_next_free_sgpr 102
		.amdhsa_accum_offset 256
		.amdhsa_reserve_vcc 1
		.amdhsa_float_round_mode_32 0
		.amdhsa_float_round_mode_16_64 0
		.amdhsa_float_denorm_mode_32 3
		.amdhsa_float_denorm_mode_16_64 3
		.amdhsa_dx10_clamp 1
		.amdhsa_ieee_mode 1
		.amdhsa_fp16_overflow 0
		.amdhsa_tg_split 0
		.amdhsa_exception_fp_ieee_invalid_op 0
		.amdhsa_exception_fp_denorm_src 0
		.amdhsa_exception_fp_ieee_div_zero 0
		.amdhsa_exception_fp_ieee_overflow 0
		.amdhsa_exception_fp_ieee_underflow 0
		.amdhsa_exception_fp_ieee_inexact 0
		.amdhsa_exception_int_div_zero 0
	.end_amdhsa_kernel

; __global__ void __launch_bounds__(512, 2) k_mega(P p) {
;   extern __shared__ __attribute__((aligned(16))) char smem[];
amdhsa.kernels:
  - .agpr_count:     0
    .args:
      - .offset:         0
        .size:           536
        .value_kind:     by_value
      - .offset:         536
        .size:           4
        .value_kind:     hidden_block_count_x
      - .offset:         540
        .size:           4
        .value_kind:     hidden_block_count_y
      - .offset:         544
        .size:           4
        .value_kind:     hidden_block_count_z
      - .offset:         548
        .size:           2
        .value_kind:     hidden_group_size_x
      - .offset:         550
        .size:           2
        .value_kind:     hidden_group_size_y
      - .offset:         552
        .size:           2
        .value_kind:     hidden_group_size_z
      - .offset:         554
        .size:           2
        .value_kind:     hidden_remainder_x
      - .offset:         556
        .size:           2
        .value_kind:     hidden_remainder_y
      - .offset:         558
        .size:           2
        .value_kind:     hidden_remainder_z
      - .offset:         576
        .size:           8
        .value_kind:     hidden_global_offset_x
      - .offset:         584
        .size:           8
        .value_kind:     hidden_global_offset_y
      - .offset:         592
        .size:           8
        .value_kind:     hidden_global_offset_z
      - .offset:         600
        .size:           2
        .value_kind:     hidden_grid_dims
      - .offset:         624
        .size:           8
        .value_kind:     hidden_multigrid_sync_arg
      - .offset:         656
        .size:           4
        .value_kind:     hidden_dynamic_lds_size
    .group_segment_fixed_size: 8448
    .kernarg_segment_align: 8
    .kernarg_segment_size: 792
    .language:       OpenCL C
    .language_version:
      - 2
      - 0
    .max_flat_workgroup_size: 512
    .name:           _Z6k_mega1P
    .private_segment_fixed_size: 0
    .sgpr_count:     108
    .sgpr_spill_count: 44
    .symbol:         _Z6k_mega1P.kd
    .uniform_work_group_size: 1
    .uses_dynamic_stack: false
    .vgpr_count:     256
    .vgpr_spill_count: 0
    .wavefront_size: 64
